# baseline (speedup 1.0000x reference)
; __device__ __forceinline__ void retq_item(const Params& p, int item, char* lds, int tid) {
;     ...
;   float sm = 0.f;
; #pragma unroll
;   for (int et = 0; et < 16; ++et) sm += (o[et][0] + o[et][1]) + (o[et][2] + o[et][3]);
;   sm += __shfl_xor(sm, 16);
;   sm += __shfl_xor(sm, 32);
;   const float mu = sm * (1.0f / 256.0f);
;   float q2 = 0.f;
; #pragma unroll
;   for (int et = 0; et < 16; ++et)
; #pragma unroll
;     for (int j = 0; j < 4; ++j) { float d = o[et][j] - mu; q2 += d * d; }
;   q2 += __shfl_xor(q2, 16);
;   q2 += __shfl_xor(q2, 32);
;   const float rstd = rsqrtf(q2 * (1.0f / 256.0f) + LN_EPS);
.LBB0_230:
	v_mov_b32_e32 v2, v57
	v_mov_b32_e32 v3, v58
	s_waitcnt vmcnt(0) lgkmcnt(0)
	v_mov_b32_e32 v68, v56
	v_mov_b32_e32 v69, v59
	v_pk_add_f32 v[2:3], v[2:3], v[68:69]
	v_mov_b32_e32 v68, v53
	v_mov_b32_e32 v69, v54
	v_mov_b32_e32 v70, v52
	v_mov_b32_e32 v71, v55
	v_pk_add_f32 v[68:69], v[68:69], v[70:71]
	v_add_f32_e32 v0, v2, v3
	v_pk_add_f32 v[68:69], v[68:69], v[68:69] op_sel_hi:[0,1]
	v_add_f32_e32 v3, 0, v0
	v_add_f32_e32 v71, v48, v49
	v_add_f32_e32 v73, v50, v51
	v_mov_b32_e32 v70, v44
	v_mov_b32_e32 v72, v45
	v_mov_b32_e32 v68, v46
	v_mov_b32_e32 v2, v47
	v_pk_add_f32 v[70:71], v[70:71], v[72:73]
	v_pk_add_f32 v[2:3], v[68:69], v[2:3]
	v_mov_b32_e32 v68, v41
	v_pk_add_f32 v[2:3], v[70:71], v[2:3]
	v_mov_b32_e32 v69, v42
	v_mov_b32_e32 v70, v40
	v_mov_b32_e32 v71, v43
	v_pk_add_f32 v[68:69], v[68:69], v[70:71]
	v_pk_add_f32 v[2:3], v[2:3], v[2:3] op_sel_hi:[0,1]
	v_pk_add_f32 v[68:69], v[68:69], v[68:69] op_sel_hi:[0,1]
	v_add_f32_e32 v71, v36, v37
	v_add_f32_e32 v73, v38, v39
	v_mov_b32_e32 v70, v32
	v_mov_b32_e32 v72, v33
	v_mov_b32_e32 v68, v34
	v_mov_b32_e32 v2, v35
	v_pk_add_f32 v[70:71], v[70:71], v[72:73]
	v_pk_add_f32 v[2:3], v[68:69], v[2:3]
	v_mov_b32_e32 v68, v29
	v_pk_add_f32 v[2:3], v[70:71], v[2:3]
	v_mov_b32_e32 v69, v30
	v_mov_b32_e32 v70, v28
	v_mov_b32_e32 v71, v31
	v_pk_add_f32 v[68:69], v[68:69], v[70:71]
	v_pk_add_f32 v[2:3], v[2:3], v[2:3] op_sel_hi:[0,1]
	v_pk_add_f32 v[68:69], v[68:69], v[68:69] op_sel_hi:[0,1]
	v_add_f32_e32 v71, v24, v25
	v_add_f32_e32 v73, v26, v27
	v_mov_b32_e32 v70, v20
	v_mov_b32_e32 v72, v21
	v_mov_b32_e32 v68, v22
	v_mov_b32_e32 v2, v23
	v_pk_add_f32 v[70:71], v[70:71], v[72:73]
	v_pk_add_f32 v[2:3], v[68:69], v[2:3]
	v_mov_b32_e32 v68, v17
	v_pk_add_f32 v[2:3], v[70:71], v[2:3]
	v_mov_b32_e32 v69, v18
	v_mov_b32_e32 v70, v16
	v_mov_b32_e32 v71, v19
	v_pk_add_f32 v[68:69], v[68:69], v[70:71]
	v_pk_add_f32 v[2:3], v[2:3], v[2:3] op_sel_hi:[0,1]
	v_pk_add_f32 v[68:69], v[68:69], v[68:69] op_sel_hi:[0,1]
	v_add_f32_e32 v71, v12, v13
	v_add_f32_e32 v73, v14, v15
	v_mov_b32_e32 v70, v8
	v_mov_b32_e32 v72, v9
	v_mov_b32_e32 v68, v10
	v_mov_b32_e32 v2, v11
	v_pk_add_f32 v[70:71], v[70:71], v[72:73]
	v_pk_add_f32 v[2:3], v[68:69], v[2:3]
	v_mov_b32_e32 v68, v5
	v_pk_add_f32 v[2:3], v[70:71], v[2:3]
	v_mov_b32_e32 v69, v6
	v_mov_b32_e32 v70, v4
	v_mov_b32_e32 v71, v7
	v_pk_add_f32 v[68:69], v[68:69], v[70:71]
	v_pk_add_f32 v[2:3], v[2:3], v[2:3] op_sel_hi:[0,1]
	v_pk_add_f32 v[68:69], v[68:69], v[68:69] op_sel_hi:[0,1]
	v_add_f32_e32 v71, v64, v65
	v_add_f32_e32 v73, v66, v67
	v_mov_b32_e32 v70, v60
	v_mov_b32_e32 v72, v61
	v_mov_b32_e32 v68, v62
	v_mov_b32_e32 v2, v63
	v_pk_add_f32 v[70:71], v[70:71], v[72:73]
	v_pk_add_f32 v[2:3], v[68:69], v[2:3]
	v_cmp_lt_i32_e32 vcc, v177, v180
	v_pk_add_f32 v[2:3], v[70:71], v[2:3]
	s_lshl_b32 s96, s36, 1
	v_add_f32_e32 v0, v2, v3
	v_cndmask_b32_e32 v2, v176, v177, vcc
	v_lshlrev_b32_e32 v70, 2, v2
	ds_bpermute_b32 v2, v70, v0
	v_cmp_lt_i32_e32 vcc, v179, v180
	v_mov_b32_e32 v137, v1
	s_mov_b64 s[0:1], 0x3000
	s_waitcnt lgkmcnt(0)
	v_add_f32_e32 v0, v0, v2
	v_cndmask_b32_e32 v2, v176, v179, vcc
	v_lshlrev_b32_e32 v71, 2, v2
	ds_bpermute_b32 v2, v71, v0
	s_waitcnt lgkmcnt(0)
	v_add_f32_e32 v2, v0, v2
	v_fmac_f32_e32 v57, 0xbb800000, v2
	v_fmac_f32_e32 v56, 0xbb800000, v2
	v_mul_f32_e32 v72, v57, v57
	v_fmac_f32_e32 v72, v56, v56
	v_fmac_f32_e32 v58, 0xbb800000, v2
	v_fmac_f32_e32 v72, v58, v58
	v_fmac_f32_e32 v59, 0xbb800000, v2
	v_fmac_f32_e32 v72, v59, v59
	v_fmac_f32_e32 v52, 0xbb800000, v2
	v_fmac_f32_e32 v72, v52, v52
	v_fmac_f32_e32 v53, 0xbb800000, v2
	v_fmac_f32_e32 v72, v53, v53
	v_fmac_f32_e32 v54, 0xbb800000, v2
	v_fmac_f32_e32 v72, v54, v54
	v_fmac_f32_e32 v55, 0xbb800000, v2
	v_fmac_f32_e32 v72, v55, v55
	v_fmac_f32_e32 v48, 0xbb800000, v2
	v_fmac_f32_e32 v72, v48, v48
	v_fmac_f32_e32 v49, 0xbb800000, v2
	v_fmac_f32_e32 v72, v49, v49
	v_fmac_f32_e32 v50, 0xbb800000, v2
	v_fmac_f32_e32 v72, v50, v50
	v_fmac_f32_e32 v51, 0xbb800000, v2
	v_fmac_f32_e32 v72, v51, v51
	v_fmac_f32_e32 v44, 0xbb800000, v2
	v_fmac_f32_e32 v72, v44, v44
	v_fmac_f32_e32 v45, 0xbb800000, v2
	v_fmac_f32_e32 v72, v45, v45
	v_fmac_f32_e32 v46, 0xbb800000, v2
	v_fmac_f32_e32 v72, v46, v46
	v_fmac_f32_e32 v47, 0xbb800000, v2
	v_fmac_f32_e32 v72, v47, v47
	v_fmac_f32_e32 v40, 0xbb800000, v2
	v_fmac_f32_e32 v72, v40, v40
	v_fmac_f32_e32 v41, 0xbb800000, v2
	v_fmac_f32_e32 v72, v41, v41
	v_fmac_f32_e32 v42, 0xbb800000, v2
	v_fmac_f32_e32 v72, v42, v42
	v_fmac_f32_e32 v43, 0xbb800000, v2
	v_fmac_f32_e32 v72, v43, v43
	v_fmac_f32_e32 v36, 0xbb800000, v2
	v_fmac_f32_e32 v72, v36, v36
	v_fmac_f32_e32 v37, 0xbb800000, v2
	v_fmac_f32_e32 v72, v37, v37
	v_fmac_f32_e32 v38, 0xbb800000, v2
	v_fmac_f32_e32 v72, v38, v38
	v_fmac_f32_e32 v39, 0xbb800000, v2
	v_fmac_f32_e32 v72, v39, v39
	v_fmac_f32_e32 v32, 0xbb800000, v2
	v_fmac_f32_e32 v72, v32, v32
	v_fmac_f32_e32 v33, 0xbb800000, v2
	v_fmac_f32_e32 v72, v33, v33
	v_fmac_f32_e32 v34, 0xbb800000, v2
	v_fmac_f32_e32 v72, v34, v34
	v_fmac_f32_e32 v35, 0xbb800000, v2
	v_fmac_f32_e32 v72, v35, v35
	v_fmac_f32_e32 v28, 0xbb800000, v2
	v_fmac_f32_e32 v72, v28, v28
	v_fmac_f32_e32 v29, 0xbb800000, v2
	v_fmac_f32_e32 v72, v29, v29
	v_fmac_f32_e32 v30, 0xbb800000, v2
	v_fmac_f32_e32 v72, v30, v30
	v_fmac_f32_e32 v31, 0xbb800000, v2
	v_fmac_f32_e32 v72, v31, v31
	v_fmac_f32_e32 v24, 0xbb800000, v2
	v_fmac_f32_e32 v72, v24, v24
	v_fmac_f32_e32 v25, 0xbb800000, v2
	v_fmac_f32_e32 v72, v25, v25
	v_fmac_f32_e32 v26, 0xbb800000, v2
	v_fmac_f32_e32 v72, v26, v26
	v_fmac_f32_e32 v27, 0xbb800000, v2
	v_fmac_f32_e32 v72, v27, v27
; __device__ __forceinline__ float bflo(unsigned u) { return __uint_as_float(u << 16); }
; __device__ __forceinline__ float bfhi(unsigned u) { return __uint_as_float(u & 0xffff0000u); }
; __device__ __forceinline__ void retq_item(const Params& p, int item, char* lds, int tid) {
;     ...
;   float q2 = 0.f;
; #pragma unroll
;   for (int et = 0; et < 16; ++et)
; #pragma unroll
;     for (int j = 0; j < 4; ++j) { float d = o[et][j] - mu; q2 += d * d; }
;   q2 += __shfl_xor(q2, 16);
;   q2 += __shfl_xor(q2, 32);
;   const float rstd = rsqrtf(q2 * (1.0f / 256.0f) + LN_EPS);
;   const u16* grow = proj + (long)t * INWP + OFF_RG + h * 256 + fq * 4;
;   u16* mix = WSP(u16, WS_MIX) + ((long)(b * 2048 + t)) * D + h * 256 + fq * 4;
; #pragma unroll
;   for (int et = 0; et < 16; ++et) {
;     u32x2 graw = *reinterpret_cast<const u32x2*>(grow + 16 * et);
;     float gv[4] = {bflo(graw[0]), bfhi(graw[0]), bflo(graw[1]), bfhi(graw[1])};
;     float y[4];
; #pragma unroll
;     for (int j = 0; j < 4; ++j) y[j] = (o[et][j] - mu) * rstd * (gv[j] / (1.0f + __expf(-gv[j])));
;     *reinterpret_cast<u32x2*>(mix + 16 * et) = u32x2{pk2(y[0], y[1]), pk2(y[2], y[3])};
	v_fmac_f32_e32 v20, 0xbb800000, v2
	v_fmac_f32_e32 v72, v20, v20
	v_fmac_f32_e32 v21, 0xbb800000, v2
	v_fmac_f32_e32 v72, v21, v21
	v_fmac_f32_e32 v22, 0xbb800000, v2
	v_fmac_f32_e32 v72, v22, v22
	v_fmac_f32_e32 v23, 0xbb800000, v2
	v_fmac_f32_e32 v72, v23, v23
	v_fmac_f32_e32 v16, 0xbb800000, v2
	v_fmac_f32_e32 v72, v16, v16
	v_fmac_f32_e32 v17, 0xbb800000, v2
	v_fmac_f32_e32 v72, v17, v17
	v_fmac_f32_e32 v18, 0xbb800000, v2
	v_fmac_f32_e32 v72, v18, v18
	v_fmac_f32_e32 v19, 0xbb800000, v2
	v_fmac_f32_e32 v72, v19, v19
	v_fmac_f32_e32 v12, 0xbb800000, v2
	v_fmac_f32_e32 v72, v12, v12
	v_fmac_f32_e32 v13, 0xbb800000, v2
	v_fmac_f32_e32 v72, v13, v13
	v_fmac_f32_e32 v14, 0xbb800000, v2
	v_fmac_f32_e32 v72, v14, v14
	v_fmac_f32_e32 v15, 0xbb800000, v2
	v_fmac_f32_e32 v72, v15, v15
	v_fmac_f32_e32 v8, 0xbb800000, v2
	v_fmac_f32_e32 v72, v8, v8
	v_fmac_f32_e32 v9, 0xbb800000, v2
	v_fmac_f32_e32 v72, v9, v9
	v_fmac_f32_e32 v10, 0xbb800000, v2
	v_fmac_f32_e32 v72, v10, v10
	v_fmac_f32_e32 v11, 0xbb800000, v2
	v_fmac_f32_e32 v72, v11, v11
	v_fmac_f32_e32 v4, 0xbb800000, v2
	v_fmac_f32_e32 v72, v4, v4
	v_fmac_f32_e32 v5, 0xbb800000, v2
	v_mul_f32_e32 v0, 0x3b800000, v2
	v_fmac_f32_e32 v72, v5, v5
	v_fmac_f32_e32 v6, 0xbb800000, v2
	v_fmac_f32_e32 v72, v6, v6
	v_fmac_f32_e32 v7, 0xbb800000, v2
	v_pk_add_f32 v[68:69], v[64:65], v[0:1] op_sel_hi:[1,0] neg_lo:[0,1] neg_hi:[0,1]
	v_fmac_f32_e32 v72, v7, v7
	v_pk_mul_f32 v[2:3], v[68:69], v[68:69]
	v_pk_add_f32 v[66:67], v[66:67], v[0:1] op_sel_hi:[1,0] neg_lo:[0,1] neg_hi:[0,1]
	v_add_f32_e32 v2, v2, v72
	v_add_f32_e32 v64, v3, v2
	v_pk_mul_f32 v[2:3], v[66:67], v[66:67]
	v_pk_add_f32 v[60:61], v[60:61], v[0:1] op_sel_hi:[1,0] neg_lo:[0,1] neg_hi:[0,1]
	v_add_f32_e32 v2, v2, v64
	v_add_f32_e32 v64, v3, v2
	v_pk_mul_f32 v[2:3], v[60:61], v[60:61]
	s_nop 0
	v_add_f32_e32 v2, v2, v64
	v_add_f32_e32 v64, v3, v2
	v_pk_add_f32 v[2:3], v[62:63], v[0:1] op_sel_hi:[1,0] neg_lo:[0,1] neg_hi:[0,1]
	s_nop 0
	v_pk_mul_f32 v[62:63], v[2:3], v[2:3]
	s_nop 0
	v_add_f32_e32 v0, v62, v64
	v_add_f32_e32 v0, v63, v0
	ds_bpermute_b32 v62, v70, v0
	s_waitcnt lgkmcnt(0)
	v_add_f32_e32 v0, v0, v62
	ds_bpermute_b32 v62, v71, v0
	s_waitcnt lgkmcnt(0)
	v_add_f32_e32 v0, v0, v62
	v_fmamk_f32 v0, v0, 0x3b800000, v167
	v_cmp_gt_f32_e32 vcc, s52, v0
	v_mul_f32_e32 v62, 0x4b800000, v0
	s_nop 0
	v_cndmask_b32_e32 v0, v0, v62, vcc
	v_rsq_f32_e32 v0, v0
	s_nop 0
	v_mul_f32_e32 v62, 0x45800000, v0
	v_cndmask_b32_e32 v0, v0, v62, vcc
	v_lshl_add_u64 v[62:63], v[138:139], 0, s[96:97]
	v_lshl_add_u64 v[70:71], v[62:63], 0, v[136:137]
	v_lshl_add_u64 v[64:65], v[70:71], 0, s[0:1]
	global_load_dwordx2 v[100:101], v[64:65], off offset:32
	global_load_dwordx2 v[102:103], v[64:65], off offset:64
	global_load_dwordx2 v[104:105], v[64:65], off offset:96
	global_load_dwordx2 v[106:107], v[64:65], off offset:128
	global_load_dwordx2 v[108:109], v[64:65], off offset:160
	global_load_dwordx2 v[110:111], v[64:65], off offset:192
	global_load_dwordx2 v[112:113], v[64:65], off offset:224
	global_load_dwordx2 v[114:115], v[64:65], off offset:256
	global_load_dwordx2 v[116:117], v[64:65], off offset:288
	global_load_dwordx2 v[118:119], v[64:65], off offset:320
	global_load_dwordx2 v[120:121], v[64:65], off offset:352
	global_load_dwordx2 v[122:123], v[64:65], off offset:384
	global_load_dwordx2 v[124:125], v[64:65], off offset:416
	global_load_dwordx2 v[126:127], v[64:65], off offset:448
	global_load_dwordx2 v[128:129], v[64:65], off offset:480
	s_movk_i32 s0, 0x3000
	v_add_co_u32_e32 v70, vcc, s0, v70
	v_mul_f32_e32 v56, v56, v0
	s_nop 0
	v_addc_co_u32_e32 v71, vcc, 0, v71, vcc
	flat_load_dwordx2 v[70:71], v[70:71]
	v_mul_f32_e32 v57, v57, v0
	v_mul_f32_e32 v58, v58, v0
	v_add_u32_e32 v62, s37, v154
	v_ashrrev_i32_e32 v63, 31, v62
	v_lshlrev_b64 v[62:63], 13, v[62:63]
	v_lshl_add_u64 v[62:63], s[6:7], 0, v[62:63]
	v_lshl_add_u64 v[62:63], v[62:63], 0, s[96:97]
	v_mul_f32_e32 v59, v59, v0
	v_lshl_add_u64 v[62:63], v[62:63], 0, v[136:137]
	v_mul_f32_e32 v52, v52, v0
	v_mul_f32_e32 v53, v53, v0
	v_mul_f32_e32 v54, v54, v0
	v_mul_f32_e32 v55, v55, v0
	v_mul_f32_e32 v48, v48, v0
	v_mul_f32_e32 v49, v49, v0
	v_mul_f32_e32 v50, v50, v0
	v_mul_f32_e32 v51, v51, v0
	v_mul_f32_e32 v44, v44, v0
	v_mul_f32_e32 v45, v45, v0
	v_mul_f32_e32 v46, v46, v0
	v_mul_f32_e32 v47, v47, v0
	v_mul_f32_e32 v40, v40, v0
	v_mul_f32_e32 v41, v41, v0
	v_mul_f32_e32 v42, v42, v0
	v_mul_f32_e32 v43, v43, v0
	v_mul_f32_e32 v36, v36, v0
	v_mul_f32_e32 v37, v37, v0
	v_mul_f32_e32 v38, v38, v0
	v_mul_f32_e32 v39, v39, v0
	v_mul_f32_e32 v32, v32, v0
	v_mul_f32_e32 v33, v33, v0
	v_mul_f32_e32 v34, v34, v0
	v_mul_f32_e32 v35, v35, v0
	v_mul_f32_e32 v28, v28, v0
	v_mul_f32_e32 v29, v29, v0
	v_mul_f32_e32 v30, v30, v0
	v_mul_f32_e32 v31, v31, v0
	v_mul_f32_e32 v24, v24, v0
	v_mul_f32_e32 v25, v25, v0
	v_mul_f32_e32 v26, v26, v0
	v_mul_f32_e32 v27, v27, v0
	v_mul_f32_e32 v20, v20, v0
	v_mul_f32_e32 v21, v21, v0
	v_mul_f32_e32 v22, v22, v0
	v_mul_f32_e32 v23, v23, v0
	v_mul_f32_e32 v16, v16, v0
	v_mul_f32_e32 v17, v17, v0
	v_mul_f32_e32 v18, v18, v0
	v_mul_f32_e32 v19, v19, v0
	v_mul_f32_e32 v12, v12, v0
	v_mul_f32_e32 v13, v13, v0
	v_mul_f32_e32 v14, v14, v0
	v_mul_f32_e32 v15, v15, v0
	v_mul_f32_e32 v8, v8, v0
	v_mul_f32_e32 v9, v9, v0
	v_mul_f32_e32 v10, v10, v0
	v_mul_f32_e32 v11, v11, v0
	v_mul_f32_e32 v4, v4, v0
	v_mul_f32_e32 v5, v5, v0
	v_mul_f32_e32 v6, v6, v0
	v_mul_f32_e32 v7, v7, v0
	v_mul_f32_e32 v2, v2, v0
	s_waitcnt vmcnt(0) lgkmcnt(0)
; __device__ __forceinline__ float bflo(unsigned u) { return __uint_as_float(u << 16); }
; __device__ __forceinline__ float bfhi(unsigned u) { return __uint_as_float(u & 0xffff0000u); }
; __device__ __forceinline__ void retq_item(const Params& p, int item, char* lds, int tid) {
;     ...
;   for (int et = 0; et < 16; ++et) {
;     u32x2 graw = *reinterpret_cast<const u32x2*>(grow + 16 * et);
;     float gv[4] = {bflo(graw[0]), bfhi(graw[0]), bflo(graw[1]), bfhi(graw[1])};
;     float y[4];
; #pragma unroll
;     for (int j = 0; j < 4; ++j) y[j] = (o[et][j] - mu) * rstd * (gv[j] / (1.0f + __expf(-gv[j])));
;     *reinterpret_cast<u32x2*>(mix + 16 * et) = u32x2{pk2(y[0], y[1]), pk2(y[2], y[3])};
;   }
	v_lshlrev_b32_e32 v72, 16, v70
	v_mul_f32_e32 v74, 0xbfb8aa3b, v72
	v_exp_f32_e32 v74, v74
	v_and_b32_e32 v70, 0xffff0000, v70
	v_lshlrev_b32_e32 v73, 16, v71
	v_and_b32_e32 v71, 0xffff0000, v71
	v_add_f32_e32 v74, 1.0, v74
	v_div_scale_f32 v75, s[0:1], v74, v74, v72
	v_rcp_f32_e32 v76, v75
	s_nop 0
	v_fma_f32 v77, -v75, v76, 1.0
	v_fmac_f32_e32 v76, v77, v76
	v_div_scale_f32 v77, vcc, v72, v74, v72
	v_mul_f32_e32 v78, v77, v76
	v_fma_f32 v79, -v75, v78, v77
	v_fmac_f32_e32 v78, v79, v76
	v_fma_f32 v75, -v75, v78, v77
	v_div_fmas_f32 v75, v75, v76, v78
	v_div_fixup_f32 v72, v75, v74, v72
	v_mul_f32_e32 v56, v72, v56
	v_mul_f32_e32 v72, 0xbfb8aa3b, v70
	v_exp_f32_e32 v72, v72
	s_nop 0
	v_add_f32_e32 v72, 1.0, v72
	v_div_scale_f32 v74, s[0:1], v72, v72, v70
	v_rcp_f32_e32 v75, v74
	s_nop 0
	v_fma_f32 v76, -v74, v75, 1.0
	v_fmac_f32_e32 v75, v76, v75
	v_div_scale_f32 v76, vcc, v70, v72, v70
	v_mul_f32_e32 v77, v76, v75
	v_fma_f32 v78, -v74, v77, v76
	v_fmac_f32_e32 v77, v78, v75
	v_fma_f32 v74, -v74, v77, v76
	v_div_fmas_f32 v74, v74, v75, v77
	v_div_fixup_f32 v70, v74, v72, v70
	v_mul_f32_e32 v57, v70, v57
	v_mul_f32_e32 v70, 0xbfb8aa3b, v73
	v_exp_f32_e32 v70, v70
	v_cvt_pk_bf16_f32 v56,v56,v57
	s_nop 0
	v_add_f32_e32 v70, 1.0, v70
	v_div_scale_f32 v72, s[0:1], v70, v70, v73
	v_rcp_f32_e32 v74, v72
	s_nop 0
	v_fma_f32 v75, -v72, v74, 1.0
	v_fmac_f32_e32 v74, v75, v74
	v_div_scale_f32 v75, vcc, v73, v70, v73
	v_mul_f32_e32 v76, v75, v74
	v_fma_f32 v77, -v72, v76, v75
	v_fmac_f32_e32 v76, v77, v74
	v_fma_f32 v72, -v72, v76, v75
	v_div_fmas_f32 v72, v72, v74, v76
	v_div_fixup_f32 v70, v72, v70, v73
	v_mul_f32_e32 v58, v70, v58
	v_mul_f32_e32 v70, 0xbfb8aa3b, v71
	v_exp_f32_e32 v70, v70
	s_nop 0
	v_add_f32_e32 v70, 1.0, v70
	v_div_scale_f32 v72, s[0:1], v70, v70, v71
	v_rcp_f32_e32 v73, v72
	s_nop 0
	v_fma_f32 v74, -v72, v73, 1.0
	v_fmac_f32_e32 v73, v74, v73
	v_div_scale_f32 v74, vcc, v71, v70, v71
	v_mul_f32_e32 v75, v74, v73
	v_fma_f32 v76, -v72, v75, v74
	v_fmac_f32_e32 v75, v76, v73
	v_fma_f32 v72, -v72, v75, v74
	v_div_fmas_f32 v72, v72, v73, v75
	v_div_fixup_f32 v70, v72, v70, v71
	v_mul_f32_e32 v59, v70, v59
	v_cvt_pk_bf16_f32 v57,v58,v59
	flat_store_dwordx2 v[62:63], v[56:57]
	v_mov_b32_e32 v56, v100
	v_mov_b32_e32 v57, v101
	v_lshlrev_b32_e32 v58, 16, v56
	v_mul_f32_e32 v70, 0xbfb8aa3b, v58
	v_exp_f32_e32 v70, v70
	v_and_b32_e32 v56, 0xffff0000, v56
	v_lshlrev_b32_e32 v59, 16, v57
	v_and_b32_e32 v57, 0xffff0000, v57
	v_add_f32_e32 v70, 1.0, v70
	v_div_scale_f32 v71, s[0:1], v70, v70, v58
	v_rcp_f32_e32 v72, v71
	s_nop 0
	v_fma_f32 v73, -v71, v72, 1.0
	v_fmac_f32_e32 v72, v73, v72
	v_div_scale_f32 v73, vcc, v58, v70, v58
	v_mul_f32_e32 v74, v73, v72
	v_fma_f32 v75, -v71, v74, v73
	v_fmac_f32_e32 v74, v75, v72
	v_fma_f32 v71, -v71, v74, v73
	v_div_fmas_f32 v71, v71, v72, v74
	v_div_fixup_f32 v58, v71, v70, v58
	v_mul_f32_e32 v52, v58, v52
	v_mul_f32_e32 v58, 0xbfb8aa3b, v56
	v_exp_f32_e32 v58, v58
	s_nop 0
	v_add_f32_e32 v58, 1.0, v58
	v_div_scale_f32 v70, s[0:1], v58, v58, v56
	v_rcp_f32_e32 v71, v70
	s_nop 0
	v_fma_f32 v72, -v70, v71, 1.0
	v_fmac_f32_e32 v71, v72, v71
	v_div_scale_f32 v72, vcc, v56, v58, v56
	v_mul_f32_e32 v73, v72, v71
	v_fma_f32 v74, -v70, v73, v72
	v_fmac_f32_e32 v73, v74, v71
	v_fma_f32 v70, -v70, v73, v72
	v_div_fmas_f32 v70, v70, v71, v73
	v_div_fixup_f32 v56, v70, v58, v56
	v_mul_f32_e32 v53, v56, v53
	v_mul_f32_e32 v56, 0xbfb8aa3b, v59
	v_exp_f32_e32 v56, v56
	v_cvt_pk_bf16_f32 v52,v52,v53
	s_nop 0
	v_add_f32_e32 v56, 1.0, v56
	v_div_scale_f32 v58, s[0:1], v56, v56, v59
	v_rcp_f32_e32 v70, v58
	s_nop 0
	v_fma_f32 v71, -v58, v70, 1.0
	v_fmac_f32_e32 v70, v71, v70
	v_div_scale_f32 v71, vcc, v59, v56, v59
	v_mul_f32_e32 v72, v71, v70
	v_fma_f32 v73, -v58, v72, v71
	v_fmac_f32_e32 v72, v73, v70
	v_fma_f32 v58, -v58, v72, v71
	v_div_fmas_f32 v58, v58, v70, v72
	v_div_fixup_f32 v56, v58, v56, v59
	v_mul_f32_e32 v54, v56, v54
	v_mul_f32_e32 v56, 0xbfb8aa3b, v57
	v_exp_f32_e32 v56, v56
	s_nop 0
	v_add_f32_e32 v56, 1.0, v56
	v_div_scale_f32 v58, s[0:1], v56, v56, v57
	v_rcp_f32_e32 v59, v58
	s_nop 0
	v_fma_f32 v70, -v58, v59, 1.0
	v_fmac_f32_e32 v59, v70, v59
	v_div_scale_f32 v70, vcc, v57, v56, v57
	v_mul_f32_e32 v71, v70, v59
	v_fma_f32 v72, -v58, v71, v70
	v_fmac_f32_e32 v71, v72, v59
	v_fma_f32 v58, -v58, v71, v70
	v_div_fmas_f32 v58, v58, v59, v71
	v_div_fixup_f32 v56, v58, v56, v57
	v_mul_f32_e32 v55, v56, v55
	v_cvt_pk_bf16_f32 v53,v54,v55
	flat_store_dwordx2 v[62:63], v[52:53] offset:32
	v_mov_b32_e32 v52, v102
	v_mov_b32_e32 v53, v103
	v_lshlrev_b32_e32 v54, 16, v52
	v_mul_f32_e32 v56, 0xbfb8aa3b, v54
	v_exp_f32_e32 v56, v56
	v_and_b32_e32 v52, 0xffff0000, v52
	v_lshlrev_b32_e32 v55, 16, v53
	v_and_b32_e32 v53, 0xffff0000, v53
	v_add_f32_e32 v56, 1.0, v56
	v_div_scale_f32 v57, s[0:1], v56, v56, v54
	v_rcp_f32_e32 v58, v57
	s_nop 0
	v_fma_f32 v59, -v57, v58, 1.0
	v_fmac_f32_e32 v58, v59, v58
	v_div_scale_f32 v59, vcc, v54, v56, v54
	v_mul_f32_e32 v70, v59, v58
	v_fma_f32 v71, -v57, v70, v59
	v_fmac_f32_e32 v70, v71, v58
	v_fma_f32 v57, -v57, v70, v59
	v_div_fmas_f32 v57, v57, v58, v70
	v_div_fixup_f32 v54, v57, v56, v54
	v_mul_f32_e32 v48, v54, v48
	v_mul_f32_e32 v54, 0xbfb8aa3b, v52
	v_exp_f32_e32 v54, v54
	s_nop 0
	v_add_f32_e32 v54, 1.0, v54
	v_div_scale_f32 v56, s[0:1], v54, v54, v52
	v_rcp_f32_e32 v57, v56
	s_nop 0
	v_fma_f32 v58, -v56, v57, 1.0
	v_fmac_f32_e32 v57, v58, v57
	v_div_scale_f32 v58, vcc, v52, v54, v52
	v_mul_f32_e32 v59, v58, v57
	v_fma_f32 v70, -v56, v59, v58
	v_fmac_f32_e32 v59, v70, v57
	v_fma_f32 v56, -v56, v59, v58
	v_div_fmas_f32 v56, v56, v57, v59
	v_div_fixup_f32 v52, v56, v54, v52
; __device__ __forceinline__ float bflo(unsigned u) { return __uint_as_float(u << 16); }
; __device__ __forceinline__ float bfhi(unsigned u) { return __uint_as_float(u & 0xffff0000u); }
; __device__ __forceinline__ void retq_item(const Params& p, int item, char* lds, int tid) {
;     ...
;   for (int et = 0; et < 16; ++et) {
;     u32x2 graw = *reinterpret_cast<const u32x2*>(grow + 16 * et);
;     float gv[4] = {bflo(graw[0]), bfhi(graw[0]), bflo(graw[1]), bfhi(graw[1])};
;     float y[4];
; #pragma unroll
;     for (int j = 0; j < 4; ++j) y[j] = (o[et][j] - mu) * rstd * (gv[j] / (1.0f + __expf(-gv[j])));
;     *reinterpret_cast<u32x2*>(mix + 16 * et) = u32x2{pk2(y[0], y[1]), pk2(y[2], y[3])};
;   }
	v_mul_f32_e32 v49, v52, v49
	v_mul_f32_e32 v52, 0xbfb8aa3b, v55
	v_exp_f32_e32 v52, v52
	v_cvt_pk_bf16_f32 v48,v48,v49
	s_nop 0
	v_add_f32_e32 v52, 1.0, v52
	v_div_scale_f32 v54, s[0:1], v52, v52, v55
	v_rcp_f32_e32 v56, v54
	s_nop 0
	v_fma_f32 v57, -v54, v56, 1.0
	v_fmac_f32_e32 v56, v57, v56
	v_div_scale_f32 v57, vcc, v55, v52, v55
	v_mul_f32_e32 v58, v57, v56
	v_fma_f32 v59, -v54, v58, v57
	v_fmac_f32_e32 v58, v59, v56
	v_fma_f32 v54, -v54, v58, v57
	v_div_fmas_f32 v54, v54, v56, v58
	v_div_fixup_f32 v52, v54, v52, v55
	v_mul_f32_e32 v50, v52, v50
	v_mul_f32_e32 v52, 0xbfb8aa3b, v53
	v_exp_f32_e32 v52, v52
	s_nop 0
	v_add_f32_e32 v52, 1.0, v52
	v_div_scale_f32 v54, s[0:1], v52, v52, v53
	v_rcp_f32_e32 v55, v54
	s_nop 0
	v_fma_f32 v56, -v54, v55, 1.0
	v_fmac_f32_e32 v55, v56, v55
	v_div_scale_f32 v56, vcc, v53, v52, v53
	v_mul_f32_e32 v57, v56, v55
	v_fma_f32 v58, -v54, v57, v56
	v_fmac_f32_e32 v57, v58, v55
	v_fma_f32 v54, -v54, v57, v56
	v_div_fmas_f32 v54, v54, v55, v57
	v_div_fixup_f32 v52, v54, v52, v53
	v_mul_f32_e32 v51, v52, v51
	v_cvt_pk_bf16_f32 v49,v50,v51
	flat_store_dwordx2 v[62:63], v[48:49] offset:64
	v_mov_b32_e32 v48, v104
	v_mov_b32_e32 v49, v105
	v_lshlrev_b32_e32 v50, 16, v48
	v_mul_f32_e32 v52, 0xbfb8aa3b, v50
	v_exp_f32_e32 v52, v52
	v_and_b32_e32 v48, 0xffff0000, v48
	v_lshlrev_b32_e32 v51, 16, v49
	v_and_b32_e32 v49, 0xffff0000, v49
	v_add_f32_e32 v52, 1.0, v52
	v_div_scale_f32 v53, s[0:1], v52, v52, v50
	v_rcp_f32_e32 v54, v53
	s_nop 0
	v_fma_f32 v55, -v53, v54, 1.0
	v_fmac_f32_e32 v54, v55, v54
	v_div_scale_f32 v55, vcc, v50, v52, v50
	v_mul_f32_e32 v56, v55, v54
	v_fma_f32 v57, -v53, v56, v55
	v_fmac_f32_e32 v56, v57, v54
	v_fma_f32 v53, -v53, v56, v55
	v_div_fmas_f32 v53, v53, v54, v56
	v_div_fixup_f32 v50, v53, v52, v50
	v_mul_f32_e32 v44, v50, v44
	v_mul_f32_e32 v50, 0xbfb8aa3b, v48
	v_exp_f32_e32 v50, v50
	s_nop 0
	v_add_f32_e32 v50, 1.0, v50
	v_div_scale_f32 v52, s[0:1], v50, v50, v48
	v_rcp_f32_e32 v53, v52
	s_nop 0
	v_fma_f32 v54, -v52, v53, 1.0
	v_fmac_f32_e32 v53, v54, v53
	v_div_scale_f32 v54, vcc, v48, v50, v48
	v_mul_f32_e32 v55, v54, v53
	v_fma_f32 v56, -v52, v55, v54
	v_fmac_f32_e32 v55, v56, v53
	v_fma_f32 v52, -v52, v55, v54
	v_div_fmas_f32 v52, v52, v53, v55
	v_div_fixup_f32 v48, v52, v50, v48
	v_mul_f32_e32 v45, v48, v45
	v_mul_f32_e32 v48, 0xbfb8aa3b, v51
	v_exp_f32_e32 v48, v48
	v_cvt_pk_bf16_f32 v44,v44,v45
	s_nop 0
	v_add_f32_e32 v48, 1.0, v48
	v_div_scale_f32 v50, s[0:1], v48, v48, v51
	v_rcp_f32_e32 v52, v50
	s_nop 0
	v_fma_f32 v53, -v50, v52, 1.0
	v_fmac_f32_e32 v52, v53, v52
	v_div_scale_f32 v53, vcc, v51, v48, v51
	v_mul_f32_e32 v54, v53, v52
	v_fma_f32 v55, -v50, v54, v53
	v_fmac_f32_e32 v54, v55, v52
	v_fma_f32 v50, -v50, v54, v53
	v_div_fmas_f32 v50, v50, v52, v54
	v_div_fixup_f32 v48, v50, v48, v51
	v_mul_f32_e32 v46, v48, v46
	v_mul_f32_e32 v48, 0xbfb8aa3b, v49
	v_exp_f32_e32 v48, v48
	s_nop 0
	v_add_f32_e32 v48, 1.0, v48
	v_div_scale_f32 v50, s[0:1], v48, v48, v49
	v_rcp_f32_e32 v51, v50
	s_nop 0
	v_fma_f32 v52, -v50, v51, 1.0
	v_fmac_f32_e32 v51, v52, v51
	v_div_scale_f32 v52, vcc, v49, v48, v49
	v_mul_f32_e32 v53, v52, v51
	v_fma_f32 v54, -v50, v53, v52
	v_fmac_f32_e32 v53, v54, v51
	v_fma_f32 v50, -v50, v53, v52
	v_div_fmas_f32 v50, v50, v51, v53
	v_div_fixup_f32 v48, v50, v48, v49
	v_mul_f32_e32 v47, v48, v47
	v_cvt_pk_bf16_f32 v45,v46,v47
	flat_store_dwordx2 v[62:63], v[44:45] offset:96
	v_mov_b32_e32 v44, v106
	v_mov_b32_e32 v45, v107
	v_lshlrev_b32_e32 v46, 16, v44
	v_mul_f32_e32 v48, 0xbfb8aa3b, v46
	v_exp_f32_e32 v48, v48
	v_and_b32_e32 v44, 0xffff0000, v44
	v_lshlrev_b32_e32 v47, 16, v45
	v_and_b32_e32 v45, 0xffff0000, v45
	v_add_f32_e32 v48, 1.0, v48
	v_div_scale_f32 v49, s[0:1], v48, v48, v46
	v_rcp_f32_e32 v50, v49
	s_nop 0
	v_fma_f32 v51, -v49, v50, 1.0
	v_fmac_f32_e32 v50, v51, v50
	v_div_scale_f32 v51, vcc, v46, v48, v46
	v_mul_f32_e32 v52, v51, v50
	v_fma_f32 v53, -v49, v52, v51
	v_fmac_f32_e32 v52, v53, v50
	v_fma_f32 v49, -v49, v52, v51
	v_div_fmas_f32 v49, v49, v50, v52
	v_div_fixup_f32 v46, v49, v48, v46
	v_mul_f32_e32 v40, v46, v40
	v_mul_f32_e32 v46, 0xbfb8aa3b, v44
	v_exp_f32_e32 v46, v46
	s_nop 0
	v_add_f32_e32 v46, 1.0, v46
	v_div_scale_f32 v48, s[0:1], v46, v46, v44
	v_rcp_f32_e32 v49, v48
	s_nop 0
	v_fma_f32 v50, -v48, v49, 1.0
	v_fmac_f32_e32 v49, v50, v49
	v_div_scale_f32 v50, vcc, v44, v46, v44
	v_mul_f32_e32 v51, v50, v49
	v_fma_f32 v52, -v48, v51, v50
	v_fmac_f32_e32 v51, v52, v49
	v_fma_f32 v48, -v48, v51, v50
	v_div_fmas_f32 v48, v48, v49, v51
	v_div_fixup_f32 v44, v48, v46, v44
	v_mul_f32_e32 v41, v44, v41
	v_mul_f32_e32 v44, 0xbfb8aa3b, v47
	v_exp_f32_e32 v44, v44
	v_cvt_pk_bf16_f32 v40,v40,v41
	s_nop 0
	v_add_f32_e32 v44, 1.0, v44
	v_div_scale_f32 v46, s[0:1], v44, v44, v47
	v_rcp_f32_e32 v48, v46
	s_nop 0
	v_fma_f32 v49, -v46, v48, 1.0
	v_fmac_f32_e32 v48, v49, v48
	v_div_scale_f32 v49, vcc, v47, v44, v47
	v_mul_f32_e32 v50, v49, v48
	v_fma_f32 v51, -v46, v50, v49
	v_fmac_f32_e32 v50, v51, v48
	v_fma_f32 v46, -v46, v50, v49
	v_div_fmas_f32 v46, v46, v48, v50
	v_div_fixup_f32 v44, v46, v44, v47
	v_mul_f32_e32 v42, v44, v42
	v_mul_f32_e32 v44, 0xbfb8aa3b, v45
	v_exp_f32_e32 v44, v44
	s_nop 0
	v_add_f32_e32 v44, 1.0, v44
	v_div_scale_f32 v46, s[0:1], v44, v44, v45
	v_rcp_f32_e32 v47, v46
	s_nop 0
	v_fma_f32 v48, -v46, v47, 1.0
	v_fmac_f32_e32 v47, v48, v47
	v_div_scale_f32 v48, vcc, v45, v44, v45
	v_mul_f32_e32 v49, v48, v47
	v_fma_f32 v50, -v46, v49, v48
	v_fmac_f32_e32 v49, v50, v47
	v_fma_f32 v46, -v46, v49, v48
	v_div_fmas_f32 v46, v46, v47, v49
	v_div_fixup_f32 v44, v46, v44, v45
	v_mul_f32_e32 v43, v44, v43
	v_cvt_pk_bf16_f32 v41,v42,v43
; __device__ __forceinline__ float bflo(unsigned u) { return __uint_as_float(u << 16); }
; __device__ __forceinline__ float bfhi(unsigned u) { return __uint_as_float(u & 0xffff0000u); }
; __device__ __forceinline__ void retq_item(const Params& p, int item, char* lds, int tid) {
;     ...
;   for (int et = 0; et < 16; ++et) {
;     u32x2 graw = *reinterpret_cast<const u32x2*>(grow + 16 * et);
;     float gv[4] = {bflo(graw[0]), bfhi(graw[0]), bflo(graw[1]), bfhi(graw[1])};
;     float y[4];
; #pragma unroll
;     for (int j = 0; j < 4; ++j) y[j] = (o[et][j] - mu) * rstd * (gv[j] / (1.0f + __expf(-gv[j])));
;     *reinterpret_cast<u32x2*>(mix + 16 * et) = u32x2{pk2(y[0], y[1]), pk2(y[2], y[3])};
;   }
	flat_store_dwordx2 v[62:63], v[40:41] offset:128
	v_mov_b32_e32 v40, v108
	v_mov_b32_e32 v41, v109
	v_lshlrev_b32_e32 v42, 16, v40
	v_mul_f32_e32 v44, 0xbfb8aa3b, v42
	v_exp_f32_e32 v44, v44
	v_and_b32_e32 v40, 0xffff0000, v40
	v_lshlrev_b32_e32 v43, 16, v41
	v_and_b32_e32 v41, 0xffff0000, v41
	v_add_f32_e32 v44, 1.0, v44
	v_div_scale_f32 v45, s[0:1], v44, v44, v42
	v_rcp_f32_e32 v46, v45
	s_nop 0
	v_fma_f32 v47, -v45, v46, 1.0
	v_fmac_f32_e32 v46, v47, v46
	v_div_scale_f32 v47, vcc, v42, v44, v42
	v_mul_f32_e32 v48, v47, v46
	v_fma_f32 v49, -v45, v48, v47
	v_fmac_f32_e32 v48, v49, v46
	v_fma_f32 v45, -v45, v48, v47
	v_div_fmas_f32 v45, v45, v46, v48
	v_div_fixup_f32 v42, v45, v44, v42
	v_mul_f32_e32 v36, v42, v36
	v_mul_f32_e32 v42, 0xbfb8aa3b, v40
	v_exp_f32_e32 v42, v42
	s_nop 0
	v_add_f32_e32 v42, 1.0, v42
	v_div_scale_f32 v44, s[0:1], v42, v42, v40
	v_rcp_f32_e32 v45, v44
	s_nop 0
	v_fma_f32 v46, -v44, v45, 1.0
	v_fmac_f32_e32 v45, v46, v45
	v_div_scale_f32 v46, vcc, v40, v42, v40
	v_mul_f32_e32 v47, v46, v45
	v_fma_f32 v48, -v44, v47, v46
	v_fmac_f32_e32 v47, v48, v45
	v_fma_f32 v44, -v44, v47, v46
	v_div_fmas_f32 v44, v44, v45, v47
	v_div_fixup_f32 v40, v44, v42, v40
	v_mul_f32_e32 v37, v40, v37
	v_mul_f32_e32 v40, 0xbfb8aa3b, v43
	v_exp_f32_e32 v40, v40
	v_cvt_pk_bf16_f32 v36,v36,v37
	s_nop 0
	v_add_f32_e32 v40, 1.0, v40
	v_div_scale_f32 v42, s[0:1], v40, v40, v43
	v_rcp_f32_e32 v44, v42
	s_nop 0
	v_fma_f32 v45, -v42, v44, 1.0
	v_fmac_f32_e32 v44, v45, v44
	v_div_scale_f32 v45, vcc, v43, v40, v43
	v_mul_f32_e32 v46, v45, v44
	v_fma_f32 v47, -v42, v46, v45
	v_fmac_f32_e32 v46, v47, v44
	v_fma_f32 v42, -v42, v46, v45
	v_div_fmas_f32 v42, v42, v44, v46
	v_div_fixup_f32 v40, v42, v40, v43
	v_mul_f32_e32 v38, v40, v38
	v_mul_f32_e32 v40, 0xbfb8aa3b, v41
	v_exp_f32_e32 v40, v40
	s_nop 0
	v_add_f32_e32 v40, 1.0, v40
	v_div_scale_f32 v42, s[0:1], v40, v40, v41
	v_rcp_f32_e32 v43, v42
	s_nop 0
	v_fma_f32 v44, -v42, v43, 1.0
	v_fmac_f32_e32 v43, v44, v43
	v_div_scale_f32 v44, vcc, v41, v40, v41
	v_mul_f32_e32 v45, v44, v43
	v_fma_f32 v46, -v42, v45, v44
	v_fmac_f32_e32 v45, v46, v43
	v_fma_f32 v42, -v42, v45, v44
	v_div_fmas_f32 v42, v42, v43, v45
	v_div_fixup_f32 v40, v42, v40, v41
	v_mul_f32_e32 v39, v40, v39
	v_cvt_pk_bf16_f32 v37,v38,v39
	flat_store_dwordx2 v[62:63], v[36:37] offset:160
	v_mov_b32_e32 v36, v110
	v_mov_b32_e32 v37, v111
	v_lshlrev_b32_e32 v38, 16, v36
	v_mul_f32_e32 v40, 0xbfb8aa3b, v38
	v_exp_f32_e32 v40, v40
	v_and_b32_e32 v36, 0xffff0000, v36
	v_lshlrev_b32_e32 v39, 16, v37
	v_and_b32_e32 v37, 0xffff0000, v37
	v_add_f32_e32 v40, 1.0, v40
	v_div_scale_f32 v41, s[0:1], v40, v40, v38
	v_rcp_f32_e32 v42, v41
	s_nop 0
	v_fma_f32 v43, -v41, v42, 1.0
	v_fmac_f32_e32 v42, v43, v42
	v_div_scale_f32 v43, vcc, v38, v40, v38
	v_mul_f32_e32 v44, v43, v42
	v_fma_f32 v45, -v41, v44, v43
	v_fmac_f32_e32 v44, v45, v42
	v_fma_f32 v41, -v41, v44, v43
	v_div_fmas_f32 v41, v41, v42, v44
	v_div_fixup_f32 v38, v41, v40, v38
	v_mul_f32_e32 v32, v38, v32
	v_mul_f32_e32 v38, 0xbfb8aa3b, v36
	v_exp_f32_e32 v38, v38
	s_nop 0
	v_add_f32_e32 v38, 1.0, v38
	v_div_scale_f32 v40, s[0:1], v38, v38, v36
	v_rcp_f32_e32 v41, v40
	s_nop 0
	v_fma_f32 v42, -v40, v41, 1.0
	v_fmac_f32_e32 v41, v42, v41
	v_div_scale_f32 v42, vcc, v36, v38, v36
	v_mul_f32_e32 v43, v42, v41
	v_fma_f32 v44, -v40, v43, v42
	v_fmac_f32_e32 v43, v44, v41
	v_fma_f32 v40, -v40, v43, v42
	v_div_fmas_f32 v40, v40, v41, v43
	v_div_fixup_f32 v36, v40, v38, v36
	v_mul_f32_e32 v33, v36, v33
	v_mul_f32_e32 v36, 0xbfb8aa3b, v39
	v_exp_f32_e32 v36, v36
	v_cvt_pk_bf16_f32 v32,v32,v33
	s_nop 0
	v_add_f32_e32 v36, 1.0, v36
	v_div_scale_f32 v38, s[0:1], v36, v36, v39
	v_rcp_f32_e32 v40, v38
	s_nop 0
	v_fma_f32 v41, -v38, v40, 1.0
	v_fmac_f32_e32 v40, v41, v40
	v_div_scale_f32 v41, vcc, v39, v36, v39
	v_mul_f32_e32 v42, v41, v40
	v_fma_f32 v43, -v38, v42, v41
	v_fmac_f32_e32 v42, v43, v40
	v_fma_f32 v38, -v38, v42, v41
	v_div_fmas_f32 v38, v38, v40, v42
	v_div_fixup_f32 v36, v38, v36, v39
	v_mul_f32_e32 v34, v36, v34
	v_mul_f32_e32 v36, 0xbfb8aa3b, v37
	v_exp_f32_e32 v36, v36
	s_nop 0
	v_add_f32_e32 v36, 1.0, v36
	v_div_scale_f32 v38, s[0:1], v36, v36, v37
	v_rcp_f32_e32 v39, v38
	s_nop 0
	v_fma_f32 v40, -v38, v39, 1.0
	v_fmac_f32_e32 v39, v40, v39
	v_div_scale_f32 v40, vcc, v37, v36, v37
	v_mul_f32_e32 v41, v40, v39
	v_fma_f32 v42, -v38, v41, v40
	v_fmac_f32_e32 v41, v42, v39
	v_fma_f32 v38, -v38, v41, v40
	v_div_fmas_f32 v38, v38, v39, v41
	v_div_fixup_f32 v36, v38, v36, v37
	v_mul_f32_e32 v35, v36, v35
	v_cvt_pk_bf16_f32 v33,v34,v35
	flat_store_dwordx2 v[62:63], v[32:33] offset:192
	v_mov_b32_e32 v32, v112
	v_mov_b32_e32 v33, v113
	v_lshlrev_b32_e32 v34, 16, v32
	v_mul_f32_e32 v36, 0xbfb8aa3b, v34
	v_exp_f32_e32 v36, v36
	v_and_b32_e32 v32, 0xffff0000, v32
	v_lshlrev_b32_e32 v35, 16, v33
	v_and_b32_e32 v33, 0xffff0000, v33
	v_add_f32_e32 v36, 1.0, v36
	v_div_scale_f32 v37, s[0:1], v36, v36, v34
	v_rcp_f32_e32 v38, v37
	s_nop 0
	v_fma_f32 v39, -v37, v38, 1.0
	v_fmac_f32_e32 v38, v39, v38
	v_div_scale_f32 v39, vcc, v34, v36, v34
	v_mul_f32_e32 v40, v39, v38
	v_fma_f32 v41, -v37, v40, v39
	v_fmac_f32_e32 v40, v41, v38
	v_fma_f32 v37, -v37, v40, v39
	v_div_fmas_f32 v37, v37, v38, v40
	v_div_fixup_f32 v34, v37, v36, v34
	v_mul_f32_e32 v28, v34, v28
	v_mul_f32_e32 v34, 0xbfb8aa3b, v32
	v_exp_f32_e32 v34, v34
	s_nop 0
	v_add_f32_e32 v34, 1.0, v34
	v_div_scale_f32 v36, s[0:1], v34, v34, v32
	v_rcp_f32_e32 v37, v36
	s_nop 0
	v_fma_f32 v38, -v36, v37, 1.0
	v_fmac_f32_e32 v37, v38, v37
	v_div_scale_f32 v38, vcc, v32, v34, v32
	v_mul_f32_e32 v39, v38, v37
	v_fma_f32 v40, -v36, v39, v38
	v_fmac_f32_e32 v39, v40, v37
; __device__ __forceinline__ float bflo(unsigned u) { return __uint_as_float(u << 16); }
; __device__ __forceinline__ float bfhi(unsigned u) { return __uint_as_float(u & 0xffff0000u); }
; __device__ __forceinline__ void retq_item(const Params& p, int item, char* lds, int tid) {
;     ...
;   for (int et = 0; et < 16; ++et) {
;     u32x2 graw = *reinterpret_cast<const u32x2*>(grow + 16 * et);
;     float gv[4] = {bflo(graw[0]), bfhi(graw[0]), bflo(graw[1]), bfhi(graw[1])};
;     float y[4];
; #pragma unroll
;     for (int j = 0; j < 4; ++j) y[j] = (o[et][j] - mu) * rstd * (gv[j] / (1.0f + __expf(-gv[j])));
;     *reinterpret_cast<u32x2*>(mix + 16 * et) = u32x2{pk2(y[0], y[1]), pk2(y[2], y[3])};
;   }
	v_fma_f32 v36, -v36, v39, v38
	v_div_fmas_f32 v36, v36, v37, v39
	v_div_fixup_f32 v32, v36, v34, v32
	v_mul_f32_e32 v29, v32, v29
	v_mul_f32_e32 v32, 0xbfb8aa3b, v35
	v_exp_f32_e32 v32, v32
	v_cvt_pk_bf16_f32 v28,v28,v29
	s_nop 0
	v_add_f32_e32 v32, 1.0, v32
	v_div_scale_f32 v34, s[0:1], v32, v32, v35
	v_rcp_f32_e32 v36, v34
	s_nop 0
	v_fma_f32 v37, -v34, v36, 1.0
	v_fmac_f32_e32 v36, v37, v36
	v_div_scale_f32 v37, vcc, v35, v32, v35
	v_mul_f32_e32 v38, v37, v36
	v_fma_f32 v39, -v34, v38, v37
	v_fmac_f32_e32 v38, v39, v36
	v_fma_f32 v34, -v34, v38, v37
	v_div_fmas_f32 v34, v34, v36, v38
	v_div_fixup_f32 v32, v34, v32, v35
	v_mul_f32_e32 v30, v32, v30
	v_mul_f32_e32 v32, 0xbfb8aa3b, v33
	v_exp_f32_e32 v32, v32
	s_nop 0
	v_add_f32_e32 v32, 1.0, v32
	v_div_scale_f32 v34, s[0:1], v32, v32, v33
	v_rcp_f32_e32 v35, v34
	s_nop 0
	v_fma_f32 v36, -v34, v35, 1.0
	v_fmac_f32_e32 v35, v36, v35
	v_div_scale_f32 v36, vcc, v33, v32, v33
	v_mul_f32_e32 v37, v36, v35
	v_fma_f32 v38, -v34, v37, v36
	v_fmac_f32_e32 v37, v38, v35
	v_fma_f32 v34, -v34, v37, v36
	v_div_fmas_f32 v34, v34, v35, v37
	v_div_fixup_f32 v32, v34, v32, v33
	v_mul_f32_e32 v31, v32, v31
	v_cvt_pk_bf16_f32 v29,v30,v31
	flat_store_dwordx2 v[62:63], v[28:29] offset:224
	v_mov_b32_e32 v28, v114
	v_mov_b32_e32 v29, v115
	v_lshlrev_b32_e32 v30, 16, v28
	v_mul_f32_e32 v32, 0xbfb8aa3b, v30
	v_exp_f32_e32 v32, v32
	v_and_b32_e32 v28, 0xffff0000, v28
	v_lshlrev_b32_e32 v31, 16, v29
	v_and_b32_e32 v29, 0xffff0000, v29
	v_add_f32_e32 v32, 1.0, v32
	v_div_scale_f32 v33, s[0:1], v32, v32, v30
	v_rcp_f32_e32 v34, v33
	s_nop 0
	v_fma_f32 v35, -v33, v34, 1.0
	v_fmac_f32_e32 v34, v35, v34
	v_div_scale_f32 v35, vcc, v30, v32, v30
	v_mul_f32_e32 v36, v35, v34
	v_fma_f32 v37, -v33, v36, v35
	v_fmac_f32_e32 v36, v37, v34
	v_fma_f32 v33, -v33, v36, v35
	v_div_fmas_f32 v33, v33, v34, v36
	v_div_fixup_f32 v30, v33, v32, v30
	v_mul_f32_e32 v24, v30, v24
	v_mul_f32_e32 v30, 0xbfb8aa3b, v28
	v_exp_f32_e32 v30, v30
	s_nop 0
	v_add_f32_e32 v30, 1.0, v30
	v_div_scale_f32 v32, s[0:1], v30, v30, v28
	v_rcp_f32_e32 v33, v32
	s_nop 0
	v_fma_f32 v34, -v32, v33, 1.0
	v_fmac_f32_e32 v33, v34, v33
	v_div_scale_f32 v34, vcc, v28, v30, v28
	v_mul_f32_e32 v35, v34, v33
	v_fma_f32 v36, -v32, v35, v34
	v_fmac_f32_e32 v35, v36, v33
	v_fma_f32 v32, -v32, v35, v34
	v_div_fmas_f32 v32, v32, v33, v35
	v_div_fixup_f32 v28, v32, v30, v28
	v_mul_f32_e32 v25, v28, v25
	v_mul_f32_e32 v28, 0xbfb8aa3b, v31
	v_exp_f32_e32 v28, v28
	v_cvt_pk_bf16_f32 v24,v24,v25
	s_nop 0
	v_add_f32_e32 v28, 1.0, v28
	v_div_scale_f32 v30, s[0:1], v28, v28, v31
	v_rcp_f32_e32 v32, v30
	s_nop 0
	v_fma_f32 v33, -v30, v32, 1.0
	v_fmac_f32_e32 v32, v33, v32
	v_div_scale_f32 v33, vcc, v31, v28, v31
	v_mul_f32_e32 v34, v33, v32
	v_fma_f32 v35, -v30, v34, v33
	v_fmac_f32_e32 v34, v35, v32
	v_fma_f32 v30, -v30, v34, v33
	v_div_fmas_f32 v30, v30, v32, v34
	v_div_fixup_f32 v28, v30, v28, v31
	v_mul_f32_e32 v26, v28, v26
	v_mul_f32_e32 v28, 0xbfb8aa3b, v29
	v_exp_f32_e32 v28, v28
	s_nop 0
	v_add_f32_e32 v28, 1.0, v28
	v_div_scale_f32 v30, s[0:1], v28, v28, v29
	v_rcp_f32_e32 v31, v30
	s_nop 0
	v_fma_f32 v32, -v30, v31, 1.0
	v_fmac_f32_e32 v31, v32, v31
	v_div_scale_f32 v32, vcc, v29, v28, v29
	v_mul_f32_e32 v33, v32, v31
	v_fma_f32 v34, -v30, v33, v32
	v_fmac_f32_e32 v33, v34, v31
	v_fma_f32 v30, -v30, v33, v32
	v_div_fmas_f32 v30, v30, v31, v33
	v_div_fixup_f32 v28, v30, v28, v29
	v_mul_f32_e32 v27, v28, v27
	v_cvt_pk_bf16_f32 v25,v26,v27
	flat_store_dwordx2 v[62:63], v[24:25] offset:256
	v_mov_b32_e32 v24, v116
	v_mov_b32_e32 v25, v117
	v_lshlrev_b32_e32 v26, 16, v24
	v_mul_f32_e32 v28, 0xbfb8aa3b, v26
	v_exp_f32_e32 v28, v28
	v_and_b32_e32 v24, 0xffff0000, v24
	v_lshlrev_b32_e32 v27, 16, v25
	v_and_b32_e32 v25, 0xffff0000, v25
	v_add_f32_e32 v28, 1.0, v28
	v_div_scale_f32 v29, s[0:1], v28, v28, v26
	v_rcp_f32_e32 v30, v29
	s_nop 0
	v_fma_f32 v31, -v29, v30, 1.0
	v_fmac_f32_e32 v30, v31, v30
	v_div_scale_f32 v31, vcc, v26, v28, v26
	v_mul_f32_e32 v32, v31, v30
	v_fma_f32 v33, -v29, v32, v31
	v_fmac_f32_e32 v32, v33, v30
	v_fma_f32 v29, -v29, v32, v31
	v_div_fmas_f32 v29, v29, v30, v32
	v_div_fixup_f32 v26, v29, v28, v26
	v_mul_f32_e32 v20, v26, v20
	v_mul_f32_e32 v26, 0xbfb8aa3b, v24
	v_exp_f32_e32 v26, v26
	s_nop 0
	v_add_f32_e32 v26, 1.0, v26
	v_div_scale_f32 v28, s[0:1], v26, v26, v24
	v_rcp_f32_e32 v29, v28
	s_nop 0
	v_fma_f32 v30, -v28, v29, 1.0
	v_fmac_f32_e32 v29, v30, v29
	v_div_scale_f32 v30, vcc, v24, v26, v24
	v_mul_f32_e32 v31, v30, v29
	v_fma_f32 v32, -v28, v31, v30
	v_fmac_f32_e32 v31, v32, v29
	v_fma_f32 v28, -v28, v31, v30
	v_div_fmas_f32 v28, v28, v29, v31
	v_div_fixup_f32 v24, v28, v26, v24
	v_mul_f32_e32 v21, v24, v21
	v_mul_f32_e32 v24, 0xbfb8aa3b, v27
	v_exp_f32_e32 v24, v24
	v_cvt_pk_bf16_f32 v20,v20,v21
	s_nop 0
	v_add_f32_e32 v24, 1.0, v24
	v_div_scale_f32 v26, s[0:1], v24, v24, v27
	v_rcp_f32_e32 v28, v26
	s_nop 0
	v_fma_f32 v29, -v26, v28, 1.0
	v_fmac_f32_e32 v28, v29, v28
	v_div_scale_f32 v29, vcc, v27, v24, v27
	v_mul_f32_e32 v30, v29, v28
	v_fma_f32 v31, -v26, v30, v29
	v_fmac_f32_e32 v30, v31, v28
	v_fma_f32 v26, -v26, v30, v29
	v_div_fmas_f32 v26, v26, v28, v30
	v_div_fixup_f32 v24, v26, v24, v27
	v_mul_f32_e32 v22, v24, v22
	v_mul_f32_e32 v24, 0xbfb8aa3b, v25
	v_exp_f32_e32 v24, v24
	s_nop 0
	v_add_f32_e32 v24, 1.0, v24
	v_div_scale_f32 v26, s[0:1], v24, v24, v25
	v_rcp_f32_e32 v27, v26
	s_nop 0
	v_fma_f32 v28, -v26, v27, 1.0
	v_fmac_f32_e32 v27, v28, v27
	v_div_scale_f32 v28, vcc, v25, v24, v25
	v_mul_f32_e32 v29, v28, v27
	v_fma_f32 v30, -v26, v29, v28
	v_fmac_f32_e32 v29, v30, v27
	v_fma_f32 v26, -v26, v29, v28
	v_div_fmas_f32 v26, v26, v27, v29
; __device__ __forceinline__ float bflo(unsigned u) { return __uint_as_float(u << 16); }
; __device__ __forceinline__ float bfhi(unsigned u) { return __uint_as_float(u & 0xffff0000u); }
; __device__ __forceinline__ void retq_item(const Params& p, int item, char* lds, int tid) {
;     ...
;   for (int et = 0; et < 16; ++et) {
;     u32x2 graw = *reinterpret_cast<const u32x2*>(grow + 16 * et);
;     float gv[4] = {bflo(graw[0]), bfhi(graw[0]), bflo(graw[1]), bfhi(graw[1])};
;     float y[4];
; #pragma unroll
;     for (int j = 0; j < 4; ++j) y[j] = (o[et][j] - mu) * rstd * (gv[j] / (1.0f + __expf(-gv[j])));
;     *reinterpret_cast<u32x2*>(mix + 16 * et) = u32x2{pk2(y[0], y[1]), pk2(y[2], y[3])};
;   }
	v_div_fixup_f32 v24, v26, v24, v25
	v_mul_f32_e32 v23, v24, v23
	v_cvt_pk_bf16_f32 v21,v22,v23
	flat_store_dwordx2 v[62:63], v[20:21] offset:288
	v_mov_b32_e32 v20, v118
	v_mov_b32_e32 v21, v119
	v_lshlrev_b32_e32 v22, 16, v20
	v_mul_f32_e32 v24, 0xbfb8aa3b, v22
	v_exp_f32_e32 v24, v24
	v_and_b32_e32 v20, 0xffff0000, v20
	v_lshlrev_b32_e32 v23, 16, v21
	v_and_b32_e32 v21, 0xffff0000, v21
	v_add_f32_e32 v24, 1.0, v24
	v_div_scale_f32 v25, s[0:1], v24, v24, v22
	v_rcp_f32_e32 v26, v25
	s_nop 0
	v_fma_f32 v27, -v25, v26, 1.0
	v_fmac_f32_e32 v26, v27, v26
	v_div_scale_f32 v27, vcc, v22, v24, v22
	v_mul_f32_e32 v28, v27, v26
	v_fma_f32 v29, -v25, v28, v27
	v_fmac_f32_e32 v28, v29, v26
	v_fma_f32 v25, -v25, v28, v27
	v_div_fmas_f32 v25, v25, v26, v28
	v_div_fixup_f32 v22, v25, v24, v22
	v_mul_f32_e32 v16, v22, v16
	v_mul_f32_e32 v22, 0xbfb8aa3b, v20
	v_exp_f32_e32 v22, v22
	s_nop 0
	v_add_f32_e32 v22, 1.0, v22
	v_div_scale_f32 v24, s[0:1], v22, v22, v20
	v_rcp_f32_e32 v25, v24
	s_nop 0
	v_fma_f32 v26, -v24, v25, 1.0
	v_fmac_f32_e32 v25, v26, v25
	v_div_scale_f32 v26, vcc, v20, v22, v20
	v_mul_f32_e32 v27, v26, v25
	v_fma_f32 v28, -v24, v27, v26
	v_fmac_f32_e32 v27, v28, v25
	v_fma_f32 v24, -v24, v27, v26
	v_div_fmas_f32 v24, v24, v25, v27
	v_div_fixup_f32 v20, v24, v22, v20
	v_mul_f32_e32 v17, v20, v17
	v_mul_f32_e32 v20, 0xbfb8aa3b, v23
	v_exp_f32_e32 v20, v20
	v_cvt_pk_bf16_f32 v16,v16,v17
	s_nop 0
	v_add_f32_e32 v20, 1.0, v20
	v_div_scale_f32 v22, s[0:1], v20, v20, v23
	v_rcp_f32_e32 v24, v22
	s_nop 0
	v_fma_f32 v25, -v22, v24, 1.0
	v_fmac_f32_e32 v24, v25, v24
	v_div_scale_f32 v25, vcc, v23, v20, v23
	v_mul_f32_e32 v26, v25, v24
	v_fma_f32 v27, -v22, v26, v25
	v_fmac_f32_e32 v26, v27, v24
	v_fma_f32 v22, -v22, v26, v25
	v_div_fmas_f32 v22, v22, v24, v26
	v_div_fixup_f32 v20, v22, v20, v23
	v_mul_f32_e32 v18, v20, v18
	v_mul_f32_e32 v20, 0xbfb8aa3b, v21
	v_exp_f32_e32 v20, v20
	s_nop 0
	v_add_f32_e32 v20, 1.0, v20
	v_div_scale_f32 v22, s[0:1], v20, v20, v21
	v_rcp_f32_e32 v23, v22
	s_nop 0
	v_fma_f32 v24, -v22, v23, 1.0
	v_fmac_f32_e32 v23, v24, v23
	v_div_scale_f32 v24, vcc, v21, v20, v21
	v_mul_f32_e32 v25, v24, v23
	v_fma_f32 v26, -v22, v25, v24
	v_fmac_f32_e32 v25, v26, v23
	v_fma_f32 v22, -v22, v25, v24
	v_div_fmas_f32 v22, v22, v23, v25
	v_div_fixup_f32 v20, v22, v20, v21
	v_mul_f32_e32 v19, v20, v19
	v_cvt_pk_bf16_f32 v17,v18,v19
	flat_store_dwordx2 v[62:63], v[16:17] offset:320
	v_mov_b32_e32 v16, v120
	v_mov_b32_e32 v17, v121
	v_lshlrev_b32_e32 v18, 16, v16
	v_mul_f32_e32 v20, 0xbfb8aa3b, v18
	v_exp_f32_e32 v20, v20
	v_and_b32_e32 v16, 0xffff0000, v16
	v_lshlrev_b32_e32 v19, 16, v17
	v_and_b32_e32 v17, 0xffff0000, v17
	v_add_f32_e32 v20, 1.0, v20
	v_div_scale_f32 v21, s[0:1], v20, v20, v18
	v_rcp_f32_e32 v22, v21
	s_nop 0
	v_fma_f32 v23, -v21, v22, 1.0
	v_fmac_f32_e32 v22, v23, v22
	v_div_scale_f32 v23, vcc, v18, v20, v18
	v_mul_f32_e32 v24, v23, v22
	v_fma_f32 v25, -v21, v24, v23
	v_fmac_f32_e32 v24, v25, v22
	v_fma_f32 v21, -v21, v24, v23
	v_div_fmas_f32 v21, v21, v22, v24
	v_div_fixup_f32 v18, v21, v20, v18
	v_mul_f32_e32 v12, v18, v12
	v_mul_f32_e32 v18, 0xbfb8aa3b, v16
	v_exp_f32_e32 v18, v18
	s_nop 0
	v_add_f32_e32 v18, 1.0, v18
	v_div_scale_f32 v20, s[0:1], v18, v18, v16
	v_rcp_f32_e32 v21, v20
	s_nop 0
	v_fma_f32 v22, -v20, v21, 1.0
	v_fmac_f32_e32 v21, v22, v21
	v_div_scale_f32 v22, vcc, v16, v18, v16
	v_mul_f32_e32 v23, v22, v21
	v_fma_f32 v24, -v20, v23, v22
	v_fmac_f32_e32 v23, v24, v21
	v_fma_f32 v20, -v20, v23, v22
	v_div_fmas_f32 v20, v20, v21, v23
	v_div_fixup_f32 v16, v20, v18, v16
	v_mul_f32_e32 v13, v16, v13
	v_mul_f32_e32 v16, 0xbfb8aa3b, v19
	v_exp_f32_e32 v16, v16
	v_cvt_pk_bf16_f32 v12,v12,v13
	s_nop 0
	v_add_f32_e32 v16, 1.0, v16
	v_div_scale_f32 v18, s[0:1], v16, v16, v19
	v_rcp_f32_e32 v20, v18
	s_nop 0
	v_fma_f32 v21, -v18, v20, 1.0
	v_fmac_f32_e32 v20, v21, v20
	v_div_scale_f32 v21, vcc, v19, v16, v19
	v_mul_f32_e32 v22, v21, v20
	v_fma_f32 v23, -v18, v22, v21
	v_fmac_f32_e32 v22, v23, v20
	v_fma_f32 v18, -v18, v22, v21
	v_div_fmas_f32 v18, v18, v20, v22
	v_div_fixup_f32 v16, v18, v16, v19
	v_mul_f32_e32 v14, v16, v14
	v_mul_f32_e32 v16, 0xbfb8aa3b, v17
	v_exp_f32_e32 v16, v16
	s_nop 0
	v_add_f32_e32 v16, 1.0, v16
	v_div_scale_f32 v18, s[0:1], v16, v16, v17
	v_rcp_f32_e32 v19, v18
	s_nop 0
	v_fma_f32 v20, -v18, v19, 1.0
	v_fmac_f32_e32 v19, v20, v19
	v_div_scale_f32 v20, vcc, v17, v16, v17
	v_mul_f32_e32 v21, v20, v19
	v_fma_f32 v22, -v18, v21, v20
	v_fmac_f32_e32 v21, v22, v19
	v_fma_f32 v18, -v18, v21, v20
	v_div_fmas_f32 v18, v18, v19, v21
	v_div_fixup_f32 v16, v18, v16, v17
	v_mul_f32_e32 v15, v16, v15
	v_cvt_pk_bf16_f32 v13,v14,v15
	flat_store_dwordx2 v[62:63], v[12:13] offset:352
	v_mov_b32_e32 v12, v122
	v_mov_b32_e32 v13, v123
	v_lshlrev_b32_e32 v14, 16, v12
	v_mul_f32_e32 v16, 0xbfb8aa3b, v14
	v_exp_f32_e32 v16, v16
	v_and_b32_e32 v12, 0xffff0000, v12
	v_lshlrev_b32_e32 v15, 16, v13
	v_and_b32_e32 v13, 0xffff0000, v13
	v_add_f32_e32 v16, 1.0, v16
	v_div_scale_f32 v17, s[0:1], v16, v16, v14
	v_rcp_f32_e32 v18, v17
	s_nop 0
	v_fma_f32 v19, -v17, v18, 1.0
	v_fmac_f32_e32 v18, v19, v18
	v_div_scale_f32 v19, vcc, v14, v16, v14
	v_mul_f32_e32 v20, v19, v18
	v_fma_f32 v21, -v17, v20, v19
	v_fmac_f32_e32 v20, v21, v18
	v_fma_f32 v17, -v17, v20, v19
	v_div_fmas_f32 v17, v17, v18, v20
	v_div_fixup_f32 v14, v17, v16, v14
	v_mul_f32_e32 v8, v14, v8
	v_mul_f32_e32 v14, 0xbfb8aa3b, v12
	v_exp_f32_e32 v14, v14
	s_nop 0
	v_add_f32_e32 v14, 1.0, v14
	v_div_scale_f32 v16, s[0:1], v14, v14, v12
	v_rcp_f32_e32 v17, v16
	s_nop 0
	v_fma_f32 v18, -v16, v17, 1.0
	v_fmac_f32_e32 v17, v18, v17
	v_div_scale_f32 v18, vcc, v12, v14, v12
; __device__ __forceinline__ float bflo(unsigned u) { return __uint_as_float(u << 16); }
; __device__ __forceinline__ float bfhi(unsigned u) { return __uint_as_float(u & 0xffff0000u); }
; __device__ __forceinline__ void retq_item(const Params& p, int item, char* lds, int tid) {
;     ...
;   for (int et = 0; et < 16; ++et) {
;     u32x2 graw = *reinterpret_cast<const u32x2*>(grow + 16 * et);
;     float gv[4] = {bflo(graw[0]), bfhi(graw[0]), bflo(graw[1]), bfhi(graw[1])};
;     float y[4];
; #pragma unroll
;     for (int j = 0; j < 4; ++j) y[j] = (o[et][j] - mu) * rstd * (gv[j] / (1.0f + __expf(-gv[j])));
;     *reinterpret_cast<u32x2*>(mix + 16 * et) = u32x2{pk2(y[0], y[1]), pk2(y[2], y[3])};
;   }
	v_mul_f32_e32 v19, v18, v17
	v_fma_f32 v20, -v16, v19, v18
	v_fmac_f32_e32 v19, v20, v17
	v_fma_f32 v16, -v16, v19, v18
	v_div_fmas_f32 v16, v16, v17, v19
	v_div_fixup_f32 v12, v16, v14, v12
	v_mul_f32_e32 v9, v12, v9
	v_mul_f32_e32 v12, 0xbfb8aa3b, v15
	v_exp_f32_e32 v12, v12
	v_cvt_pk_bf16_f32 v8,v8,v9
	s_nop 0
	v_add_f32_e32 v12, 1.0, v12
	v_div_scale_f32 v14, s[0:1], v12, v12, v15
	v_rcp_f32_e32 v16, v14
	s_nop 0
	v_fma_f32 v17, -v14, v16, 1.0
	v_fmac_f32_e32 v16, v17, v16
	v_div_scale_f32 v17, vcc, v15, v12, v15
	v_mul_f32_e32 v18, v17, v16
	v_fma_f32 v19, -v14, v18, v17
	v_fmac_f32_e32 v18, v19, v16
	v_fma_f32 v14, -v14, v18, v17
	v_div_fmas_f32 v14, v14, v16, v18
	v_div_fixup_f32 v12, v14, v12, v15
	v_mul_f32_e32 v10, v12, v10
	v_mul_f32_e32 v12, 0xbfb8aa3b, v13
	v_exp_f32_e32 v12, v12
	s_nop 0
	v_add_f32_e32 v12, 1.0, v12
	v_div_scale_f32 v14, s[0:1], v12, v12, v13
	v_rcp_f32_e32 v15, v14
	s_nop 0
	v_fma_f32 v16, -v14, v15, 1.0
	v_fmac_f32_e32 v15, v16, v15
	v_div_scale_f32 v16, vcc, v13, v12, v13
	v_mul_f32_e32 v17, v16, v15
	v_fma_f32 v18, -v14, v17, v16
	v_fmac_f32_e32 v17, v18, v15
	v_fma_f32 v14, -v14, v17, v16
	v_div_fmas_f32 v14, v14, v15, v17
	v_div_fixup_f32 v12, v14, v12, v13
	v_mul_f32_e32 v11, v12, v11
	v_cvt_pk_bf16_f32 v9,v10,v11
	flat_store_dwordx2 v[62:63], v[8:9] offset:384
	v_mov_b32_e32 v8, v124
	v_mov_b32_e32 v9, v125
	v_lshlrev_b32_e32 v10, 16, v8
	v_mul_f32_e32 v12, 0xbfb8aa3b, v10
	v_exp_f32_e32 v12, v12
	v_and_b32_e32 v8, 0xffff0000, v8
	v_lshlrev_b32_e32 v11, 16, v9
	v_and_b32_e32 v9, 0xffff0000, v9
	v_add_f32_e32 v12, 1.0, v12
	v_div_scale_f32 v13, s[0:1], v12, v12, v10
	v_rcp_f32_e32 v14, v13
	s_nop 0
	v_fma_f32 v15, -v13, v14, 1.0
	v_fmac_f32_e32 v14, v15, v14
	v_div_scale_f32 v15, vcc, v10, v12, v10
	v_mul_f32_e32 v16, v15, v14
	v_fma_f32 v17, -v13, v16, v15
	v_fmac_f32_e32 v16, v17, v14
	v_fma_f32 v13, -v13, v16, v15
	v_div_fmas_f32 v13, v13, v14, v16
	v_div_fixup_f32 v10, v13, v12, v10
	v_mul_f32_e32 v4, v10, v4
	v_mul_f32_e32 v10, 0xbfb8aa3b, v8
	v_exp_f32_e32 v10, v10
	s_nop 0
	v_add_f32_e32 v10, 1.0, v10
	v_div_scale_f32 v12, s[0:1], v10, v10, v8
	v_rcp_f32_e32 v13, v12
	s_nop 0
	v_fma_f32 v14, -v12, v13, 1.0
	v_fmac_f32_e32 v13, v14, v13
	v_div_scale_f32 v14, vcc, v8, v10, v8
	v_mul_f32_e32 v15, v14, v13
	v_fma_f32 v16, -v12, v15, v14
	v_fmac_f32_e32 v15, v16, v13
	v_fma_f32 v12, -v12, v15, v14
	v_div_fmas_f32 v12, v12, v13, v15
	v_div_fixup_f32 v8, v12, v10, v8
	v_mul_f32_e32 v5, v8, v5
	v_mul_f32_e32 v8, 0xbfb8aa3b, v11
	v_exp_f32_e32 v8, v8
	v_cvt_pk_bf16_f32 v4,v4,v5
	s_nop 0
	v_add_f32_e32 v8, 1.0, v8
	v_div_scale_f32 v10, s[0:1], v8, v8, v11
	v_rcp_f32_e32 v12, v10
	s_nop 0
	v_fma_f32 v13, -v10, v12, 1.0
	v_fmac_f32_e32 v12, v13, v12
	v_div_scale_f32 v13, vcc, v11, v8, v11
	v_mul_f32_e32 v14, v13, v12
	v_fma_f32 v15, -v10, v14, v13
	v_fmac_f32_e32 v14, v15, v12
	v_fma_f32 v10, -v10, v14, v13
	v_div_fmas_f32 v10, v10, v12, v14
	v_div_fixup_f32 v8, v10, v8, v11
	v_mul_f32_e32 v6, v8, v6
	v_mul_f32_e32 v8, 0xbfb8aa3b, v9
	v_exp_f32_e32 v8, v8
	s_nop 0
	v_add_f32_e32 v8, 1.0, v8
	v_div_scale_f32 v10, s[0:1], v8, v8, v9
	v_rcp_f32_e32 v11, v10
	s_nop 0
	v_fma_f32 v12, -v10, v11, 1.0
	v_fmac_f32_e32 v11, v12, v11
	v_div_scale_f32 v12, vcc, v9, v8, v9
	v_mul_f32_e32 v13, v12, v11
	v_fma_f32 v14, -v10, v13, v12
	v_fmac_f32_e32 v13, v14, v11
	v_fma_f32 v10, -v10, v13, v12
	v_div_fmas_f32 v10, v10, v11, v13
	v_div_fixup_f32 v8, v10, v8, v9
	v_mul_f32_e32 v7, v8, v7
	v_cvt_pk_bf16_f32 v5,v6,v7
	flat_store_dwordx2 v[62:63], v[4:5] offset:416
	v_mov_b32_e32 v4, v126
	v_mov_b32_e32 v5, v127
	v_mul_f32_e32 v8, v68, v0
	v_lshlrev_b32_e32 v6, 16, v4
	v_mul_f32_e32 v9, 0xbfb8aa3b, v6
	v_exp_f32_e32 v9, v9
	v_and_b32_e32 v4, 0xffff0000, v4
	v_lshlrev_b32_e32 v7, 16, v5
	v_and_b32_e32 v5, 0xffff0000, v5
	v_add_f32_e32 v9, 1.0, v9
	v_div_scale_f32 v10, s[0:1], v9, v9, v6
	v_rcp_f32_e32 v11, v10
	s_nop 0
	v_fma_f32 v12, -v10, v11, 1.0
	v_fmac_f32_e32 v11, v12, v11
	v_div_scale_f32 v12, vcc, v6, v9, v6
	v_mul_f32_e32 v13, v12, v11
; __device__ __forceinline__ float bflo(unsigned u) { return __uint_as_float(u << 16); }
; __device__ __forceinline__ float bfhi(unsigned u) { return __uint_as_float(u & 0xffff0000u); }
; __device__ __forceinline__ void retq_item(const Params& p, int item, char* lds, int tid) {
;     ...
;   for (int et = 0; et < 16; ++et) {
;     u32x2 graw = *reinterpret_cast<const u32x2*>(grow + 16 * et);
;     float gv[4] = {bflo(graw[0]), bfhi(graw[0]), bflo(graw[1]), bfhi(graw[1])};
;     float y[4];
; #pragma unroll
;     for (int j = 0; j < 4; ++j) y[j] = (o[et][j] - mu) * rstd * (gv[j] / (1.0f + __expf(-gv[j])));
;     *reinterpret_cast<u32x2*>(mix + 16 * et) = u32x2{pk2(y[0], y[1]), pk2(y[2], y[3])};
;   }
	v_fma_f32 v14, -v10, v13, v12
	v_fmac_f32_e32 v13, v14, v11
	v_fma_f32 v10, -v10, v13, v12
	v_div_fmas_f32 v10, v10, v11, v13
	v_div_fixup_f32 v6, v10, v9, v6
	v_mul_f32_e32 v9, 0xbfb8aa3b, v4
	v_exp_f32_e32 v9, v9
	v_mul_f32_e32 v6, v6, v8
	v_mul_f32_e32 v8, v69, v0
	v_add_f32_e32 v9, 1.0, v9
	v_div_scale_f32 v10, s[0:1], v9, v9, v4
	v_rcp_f32_e32 v11, v10
	s_nop 0
	v_fma_f32 v12, -v10, v11, 1.0
	v_fmac_f32_e32 v11, v12, v11
	v_div_scale_f32 v12, vcc, v4, v9, v4
	v_mul_f32_e32 v13, v12, v11
	v_fma_f32 v14, -v10, v13, v12
	v_fmac_f32_e32 v13, v14, v11
	v_fma_f32 v10, -v10, v13, v12
	v_div_fmas_f32 v10, v10, v11, v13
	v_div_fixup_f32 v4, v10, v9, v4
	v_mul_f32_e32 v9, 0xbfb8aa3b, v7
	v_exp_f32_e32 v9, v9
	v_mul_f32_e32 v4, v4, v8
	v_mul_f32_e32 v8, v66, v0
	v_cvt_pk_bf16_f32 v4,v6,v4
	v_add_f32_e32 v9, 1.0, v9
	v_div_scale_f32 v10, s[0:1], v9, v9, v7
	v_rcp_f32_e32 v11, v10
	s_nop 0
	v_fma_f32 v12, -v10, v11, 1.0
	v_fmac_f32_e32 v11, v12, v11
	v_div_scale_f32 v12, vcc, v7, v9, v7
	v_mul_f32_e32 v13, v12, v11
	v_fma_f32 v14, -v10, v13, v12
	v_fmac_f32_e32 v13, v14, v11
	v_fma_f32 v10, -v10, v13, v12
	v_div_fmas_f32 v10, v10, v11, v13
	v_div_fixup_f32 v7, v10, v9, v7
	v_mul_f32_e32 v9, 0xbfb8aa3b, v5
	v_exp_f32_e32 v9, v9
	v_mul_f32_e32 v7, v7, v8
	v_mul_f32_e32 v8, v67, v0
	v_add_f32_e32 v9, 1.0, v9
	v_div_scale_f32 v10, s[0:1], v9, v9, v5
	v_rcp_f32_e32 v11, v10
	s_nop 0
	v_fma_f32 v12, -v10, v11, 1.0
	v_fmac_f32_e32 v11, v12, v11
	v_div_scale_f32 v12, vcc, v5, v9, v5
	v_mul_f32_e32 v13, v12, v11
	v_fma_f32 v14, -v10, v13, v12
	v_fmac_f32_e32 v13, v14, v11
	v_fma_f32 v10, -v10, v13, v12
	v_div_fmas_f32 v10, v10, v11, v13
	v_div_fixup_f32 v5, v10, v9, v5
	v_mul_f32_e32 v5, v5, v8
	v_cvt_pk_bf16_f32 v5,v7,v5
	flat_store_dwordx2 v[62:63], v[4:5] offset:448
	v_mov_b32_e32 v4, v128
	v_mov_b32_e32 v5, v129
	v_mul_f32_e32 v8, v60, v0
	v_lshlrev_b32_e32 v6, 16, v4
	v_mul_f32_e32 v9, 0xbfb8aa3b, v6
	v_exp_f32_e32 v9, v9
	v_and_b32_e32 v4, 0xffff0000, v4
	v_lshlrev_b32_e32 v7, 16, v5
	v_and_b32_e32 v5, 0xffff0000, v5
	v_add_f32_e32 v9, 1.0, v9
	v_div_scale_f32 v10, s[0:1], v9, v9, v6
	v_rcp_f32_e32 v11, v10
	s_nop 0
	v_fma_f32 v12, -v10, v11, 1.0
	v_fmac_f32_e32 v11, v12, v11
	v_div_scale_f32 v12, vcc, v6, v9, v6
	v_mul_f32_e32 v13, v12, v11
	v_fma_f32 v14, -v10, v13, v12
	v_fmac_f32_e32 v13, v14, v11
	v_fma_f32 v10, -v10, v13, v12
	v_div_fmas_f32 v10, v10, v11, v13
	v_div_fixup_f32 v6, v10, v9, v6
	v_mul_f32_e32 v9, 0xbfb8aa3b, v4
	v_exp_f32_e32 v9, v9
	v_mul_f32_e32 v6, v6, v8
	v_mul_f32_e32 v8, v61, v0
	v_mul_f32_e32 v0, v3, v0
	v_add_f32_e32 v9, 1.0, v9
	v_div_scale_f32 v10, s[0:1], v9, v9, v4
	v_rcp_f32_e32 v11, v10
	s_nop 0
	v_fma_f32 v12, -v10, v11, 1.0
	v_fmac_f32_e32 v11, v12, v11
	v_div_scale_f32 v12, vcc, v4, v9, v4
	v_mul_f32_e32 v13, v12, v11
	v_fma_f32 v14, -v10, v13, v12
	v_fmac_f32_e32 v13, v14, v11
	v_fma_f32 v10, -v10, v13, v12
	v_div_fmas_f32 v10, v10, v11, v13
	v_div_fixup_f32 v4, v10, v9, v4
	v_mul_f32_e32 v4, v4, v8
	v_mul_f32_e32 v8, 0xbfb8aa3b, v7
	v_exp_f32_e32 v8, v8
	s_nop 0
	v_add_f32_e32 v8, 1.0, v8
	v_div_scale_f32 v9, s[0:1], v8, v8, v7
	v_rcp_f32_e32 v10, v9
	s_nop 0
	v_fma_f32 v11, -v9, v10, 1.0
	v_fmac_f32_e32 v10, v11, v10
	v_div_scale_f32 v11, vcc, v7, v8, v7
	v_mul_f32_e32 v12, v11, v10
	v_fma_f32 v13, -v9, v12, v11
	v_fmac_f32_e32 v12, v13, v10
	v_fma_f32 v9, -v9, v12, v11
	v_div_fmas_f32 v9, v9, v10, v12
	v_div_fixup_f32 v7, v9, v8, v7
	v_mul_f32_e32 v7, v7, v2
	v_mul_f32_e32 v2, 0xbfb8aa3b, v5
	v_exp_f32_e32 v2, v2
	s_nop 0
	v_add_f32_e32 v2, 1.0, v2
	v_div_scale_f32 v3, s[0:1], v2, v2, v5
	v_rcp_f32_e32 v8, v3
	s_mov_b64 s[0:1], 0
	v_fma_f32 v9, -v3, v8, 1.0
	v_fmac_f32_e32 v8, v9, v8
	v_div_scale_f32 v9, vcc, v5, v2, v5
	v_mul_f32_e32 v10, v9, v8
	v_fma_f32 v11, -v3, v10, v9
	v_fmac_f32_e32 v10, v11, v8
	v_fma_f32 v3, -v3, v10, v9
	v_div_fmas_f32 v3, v3, v8, v10
	v_div_fixup_f32 v2, v3, v2, v5
	v_mul_f32_e32 v0, v2, v0
	v_cvt_pk_bf16_f32 v2,v6,v4
	v_cvt_pk_bf16_f32 v3,v7,v0
	flat_store_dwordx2 v[62:63], v[2:3] offset:480
